# hardware transpose read (ds_read_b64_tr_b16): mc_item<2> j-loop stages V row-major with 8 ds_write_b128 (XOR-swizzled image) instead of 64 16-bit transposed writes
# speedup vs baseline: 1.0075x; 1.0004x over previous
; __device__ __forceinline__ int otid() { int t = threadIdx.x; asm volatile("" : "+v"(t)); return t; }
; #define LAS __attribute__((address_space(3)))
; template <int TY> __device__ __forceinline__ void mc_item(const Params& p, ldsp lds, int item) {
;     ...
;     const int tid = otid(), lane = tid & 63, wave = __builtin_amdgcn_readfirstlane(tid >> 6), l15 = lane & 15, q4 = lane >> 4;
;     const int bh = item >> 5, c = item & 31, b = bh >> 2, h = bh & 3, sc = c / NB, jc = c % NB, row0 = b * 2048 + c * 64;
;     ...
;     if (TY != 2) lds += LDSSHIFT;
;     ...
;     ldsp QX = lds, QH2 = lds + o_qh, KTs = lds + o_kt, VTs = lds + o_vt, Pm = lds + o_pm; LAS float* RED = (LAS float*)(lds + o_red);
;     const bf16_t* Pb = (const bf16_t*)(p.ws + WS_P);
;     constexpr int PP = TY == 2 ? NO : NE;
;     const int ecol = TY ? 256 + h * 128 : h * 64;
;     if (TY == 2) stage_rows<DK>(QX, PQ, Pb + (size_t)row0 * NO + O_Q + h * 256, NO, tid);
;     else { stage_rows<DK>(QX, PQ, (const bf16_t*)(p.ws + WS_QT) + (size_t)row0 * 768 + ecol, 768, tid);
;            stage_rows<DK>(QH2, PQ, (const bf16_t*)(p.ws + WS_QH) + (size_t)row0 * 768 + ecol, 768, tid); }
;     f32x4 acc[ET][4];
; #pragma unroll
;     for (int ei = 0; ei < ET; ++ei)
; #pragma unroll
;         for (int tk = 0; tk < 4; ++tk) acc[ei][tk] = (f32x4){0.f, 0.f, 0.f, 0.f};
;     const int voff = TY == 0 ? E_VA + h * 128 : (TY == 1 ? E_IB + h * 128 : O_V + h * 512);
;     const int tt = wave & 3, sp = wave >> 2;
;     u32x4 kr[TY == 2 ? 4 : 1], vr[TY == 2 ? 8 : 1];
;     if constexpr (TY == 2) { const size_t rowq = (size_t)b * 2048 + (sc * NB) * 64;
;         ld_rows<256>(kr, Pb + rowq * NO + O_K + h * 256, NO, tid); ld_T<512>(vr, Pb + rowq * NO + voff, NO, wave, lane); }
.LBB0_878:
	s_lshr_b32 s0, s37, 8
	s_add_i32 s1, s37, s0
	s_and_b32 s40, s1, 31
	s_ashr_i32 s20, s37, 7
	v_mov_b32_e32 v152, v161
	s_lshl_b32 s10, s20, 11
	s_lshl_b32 s11, s40, 6
	s_ashr_i32 s8, s37, 5
	s_or_b32 s58, s11, s10
	v_ashrrev_i32_e32 v0, 31, v152
	s_and_b32 s9, s8, 3
	s_mul_i32 s11, s58, 0x3000
	v_lshrrev_b32_e32 v0, 27, v0
	s_mul_hi_i32 s10, s58, 0x3000
	s_add_u32 s11, s26, s11
	v_add_u32_e32 v0, v152, v0
	s_addc_u32 s12, s27, s10
	s_lshl_b32 s59, s9, 9
	v_ashrrev_i32_e32 v62, 5, v0
	v_and_b32_e32 v0, 0xffffffe0, v0
	s_add_u32 s10, s11, s59
	v_sub_u32_e32 v60, v152, v0
	s_addc_u32 s11, s12, 0
	v_lshlrev_b32_e32 v42, 3, v60
	v_mov_b64_e32 v[4:5], s[10:11]
	v_ashrrev_i32_e32 v43, 31, v42
	v_mad_i64_i32 v[0:1], s[10:11], v62, s56, v[4:5]
	v_lshlrev_b64 v[6:7], 1, v[42:43]
	v_lshl_add_u64 v[0:1], v[0:1], 0, v[6:7]
	global_load_dwordx4 v[134:137], v[0:1], off nt
	s_movk_i32 s16, 0x108
	v_mad_u64_u32 v[8:9], s[10:11], v62, s16, v[42:43]
	v_lshl_add_u32 v8, v8, 1, 0
	s_ashr_i32 s21, s20, 31
	s_and_b32 s14, s1, 28
	s_lshl_b32 s14, s14, 6
	v_readfirstlane_b32 s60, v152
	s_ashr_i32 s12, s60, 6
	s_and_b32 s13, s1, 3
	s_lshl_b32 s9, s9, 10
	v_bfe_u32 v70, v152, 5, 1
	v_lshl_add_u32 v206, v60, 4, 0
	v_and_b32_e32 v150, 15, v152
	v_bfe_u32 v68, v152, 4, 2
	v_lshlrev_b32_e32 v138, 3, v68
	v_lshlrev_b32_e32 v151, 2, v68
	v_and_b32_e32 v153, 48, v152
	v_mul_u32_u24_e32 v225, 0x90, v150
	s_nop 0
	v_mov_b32_e32 v148, v8
	v_add_u32_e32 v0, 0x200, v152
	v_ashrrev_i32_e32 v1, 31, v0
	v_lshrrev_b32_e32 v1, 27, v1
	v_add_u32_e32 v1, v0, v1
	v_ashrrev_i32_e32 v63, 5, v1
	v_and_b32_e32 v1, 0xffffffe0, v1
	v_sub_u32_e32 v61, v0, v1
	v_lshlrev_b32_e32 v44, 3, v61
	v_ashrrev_i32_e32 v45, 31, v44
	v_mad_i64_i32 v[0:1], s[10:11], v63, s56, v[4:5]
	v_lshlrev_b64 v[8:9], 1, v[44:45]
	v_lshl_add_u64 v[0:1], v[0:1], 0, v[8:9]
	global_load_dwordx4 v[140:143], v[0:1], off nt
	v_mad_u64_u32 v[10:11], s[10:11], v63, s16, v[44:45]
	v_lshl_add_u32 v10, v10, 1, 0
	v_lshl_add_u32 v207, v61, 4, 0
	s_nop 0
	v_mov_b32_e32 v149, v10
	v_add_u32_e32 v0, 0x400, v152
	v_ashrrev_i32_e32 v1, 31, v0
	v_lshrrev_b32_e32 v1, 27, v1
	v_add_u32_e32 v1, v0, v1
	v_ashrrev_i32_e32 v64, 5, v1
	v_and_b32_e32 v1, 0xffffffe0, v1
	v_sub_u32_e32 v66, v0, v1
	v_lshlrev_b32_e32 v50, 3, v66
	v_ashrrev_i32_e32 v51, 31, v50
	v_mad_i64_i32 v[0:1], s[10:11], v64, s56, v[4:5]
	v_lshlrev_b64 v[10:11], 1, v[50:51]
	v_lshl_add_u64 v[0:1], v[0:1], 0, v[10:11]
	global_load_dwordx4 v[144:147], v[0:1], off nt
	v_mad_u64_u32 v[12:13], s[10:11], v64, s16, v[50:51]
	v_lshl_add_u32 v12, v12, 1, 0
	v_lshl_add_u32 v208, v66, 4, 0
	s_nop 0
	v_mov_b32_e32 v162, v12
	v_add_u32_e32 v0, 0x600, v152
	v_ashrrev_i32_e32 v1, 31, v0
	v_lshrrev_b32_e32 v1, 27, v1
	v_add_u32_e32 v1, v0, v1
	v_ashrrev_i32_e32 v65, 5, v1
	v_and_b32_e32 v1, 0xffffffe0, v1
	v_sub_u32_e32 v67, v0, v1
	v_lshlrev_b32_e32 v52, 3, v67
	v_ashrrev_i32_e32 v53, 31, v52
	v_mad_i64_i32 v[0:1], s[10:11], v65, s56, v[4:5]
	v_lshlrev_b64 v[4:5], 1, v[52:53]
	v_lshl_add_u64 v[0:1], v[0:1], 0, v[4:5]
	global_load_dwordx4 v[154:157], v[0:1], off nt
	v_mad_u64_u32 v[12:13], s[10:11], v65, s16, v[52:53]
	s_lshl_b64 s[10:11], s[20:21], 11
	s_or_b32 s10, s10, s14
	s_mulk_i32 s11, 0x3000
	s_mul_hi_u32 s14, s10, 0x3000
	s_add_i32 s14, s14, s11
	s_mulk_i32 s10, 0x3000
	s_add_u32 s15, s26, s10
	s_addc_u32 s14, s27, s14
	s_add_u32 s10, s15, s59
	v_lshl_add_u32 v12, v12, 1, 0
	s_addc_u32 s11, s14, 0
	s_bitset1_b32 s9, 12
	v_lshl_add_u32 v210, v67, 4, 0
	s_nop 0
	v_mov_b32_e32 v163, v12
	v_mov_b64_e32 v[0:1], s[10:11]
	v_mad_i64_i32 v[2:3], s[10:11], v62, s56, v[0:1]
	v_lshl_add_u64 v[2:3], v[2:3], 0, v[6:7]
	global_load_dwordx4 v[30:33], v[2:3], off offset:2048
	v_mad_i64_i32 v[2:3], s[10:11], v63, s56, v[0:1]
	v_lshl_add_u64 v[2:3], v[2:3], 0, v[8:9]
	global_load_dwordx4 v[34:37], v[2:3], off offset:2048
	v_mad_i64_i32 v[2:3], s[10:11], v64, s56, v[0:1]
	v_mad_i64_i32 v[0:1], s[10:11], v65, s56, v[0:1]
	v_lshl_add_u64 v[2:3], v[2:3], 0, v[10:11]
	v_lshl_add_u64 v[0:1], v[0:1], 0, v[4:5]
	s_add_u32 s10, s15, s9
	global_load_dwordx4 v[38:41], v[2:3], off offset:2048
	global_load_dwordx4 v[46:49], v[0:1], off offset:2048
	s_addc_u32 s11, s14, 0
	s_lshl_b32 s9, s12, 5
	v_and_b32_e32 v0, 31, v152
	v_and_or_b32 v69, s9, 32, v0
	s_and_b32 s9, s12, 0x1ffffffe
	v_mul_u32_u24_e32 v0, 0x1800, v69
	v_or_b32_e32 v2, s9, v70
	v_lshlrev_b32_e32 v16, 1, v0
	v_lshlrev_b32_e32 v58, 3, v2
	v_lshl_add_u64 v[0:1], s[10:11], 0, v[16:17]
	v_ashrrev_i32_e32 v59, 31, v58
	v_lshl_add_u64 v[54:55], v[58:59], 1, v[0:1]
	global_load_dwordx4 v[26:29], v[54:55], off
	global_load_dwordx4 v[22:25], v[54:55], off offset:128
	global_load_dwordx4 v[18:21], v[54:55], off offset:256
	global_load_dwordx4 v[12:15], v[54:55], off offset:384
	global_load_dwordx4 v[8:11], v[54:55], off offset:512
	global_load_dwordx4 v[4:7], v[54:55], off offset:640
	global_load_dwordx4 v[0:3], v[54:55], off offset:768
	s_nop 0
	global_load_dwordx4 v[54:57], v[54:55], off offset:896
	s_waitcnt vmcnt(15)
	ds_write_b128 v148, v[134:137]
	s_waitcnt vmcnt(14)
	ds_write_b128 v149, v[140:143]
	s_waitcnt vmcnt(13)
	ds_write_b128 v162, v[144:147]
	s_waitcnt vmcnt(12)
	ds_write_b128 v163, v[154:157]
	s_movk_i32 s9, 0x210
	v_mul_lo_u32 v203, v62, s9
	v_mul_lo_u32 v204, v63, s9
	v_mul_lo_u32 v205, v64, s9
	v_mul_lo_u32 v209, v65, s9
	s_and_b32 s9, s12, 0x3fffffe
	v_or_b32_e32 v60, s9, v70
	s_movk_i32 s9, 0x240
	v_mul_lo_u32 v60, v60, s9
	s_lshl_b32 s9, s12, 4
	v_and_or_b32 v155, s9, 48, v150
	s_ashr_i32 s9, s60, 3
	v_or_b32_e32 v60, v69, v60
	v_readlane_b32 s14, v255, 22
	s_andn2_b32 s9, s9, 31
	v_or_b32_e32 v157, s9, v151
	v_lshl_add_u32 v162, v60, 1, s14
	v_or_b32_e32 v60, s9, v150
	v_mad_u64_u32 v[60:61], s[10:11], v60, s16, v[138:139]
	v_readlane_b32 s9, v255, 23
	v_mul_u32_u24_e32 v61, 0x48, v155
	v_mul_u32_u24_e32 v67, 0x108, v155
	v_add_u32_e32 v154, s9, v153
	s_and_b32 s9, s60, 0x7fffffc0
	v_add_u32_e32 v66, 0x1080, v60
	v_add_lshl_u32 v156, v157, v61, 1
	v_or_b32_e32 v61, s9, v150
	s_movk_i32 s9, 0x90
	v_add_u32_e32 v139, s14, v153
	s_cmp_lg_u32 s13, 0
	v_add_lshl_u32 v163, v67, v138, 1
	v_lshlrev_b32_e32 v218, 1, v60
	v_lshlrev_b32_e32 v219, 1, v66
	v_or_b32_e32 v220, 16, v157
	v_or_b32_e32 v221, 17, v157
	v_or_b32_e32 v222, 18, v157
	v_or_b32_e32 v223, 3, v157
	v_or_b32_e32 v224, 19, v157
	v_mul_lo_u32 v226, v61, s9
	s_cbranch_scc0 .LBB0_897
; template <int TY> __device__ __forceinline__ void mc_item(const Params& p, ldsp lds, int item) {
;     ...
;     f32x4 acc[ET][4];
; #pragma unroll
;     for (int ei = 0; ei < ET; ++ei)
; #pragma unroll
;         for (int tk = 0; tk < 4; ++tk) acc[ei][tk] = (f32x4){0.f, 0.f, 0.f, 0.f};
;     const int voff = TY == 0 ? E_VA + h * 128 : (TY == 1 ? E_IB + h * 128 : O_V + h * 512);
;     const int tt = wave & 3, sp = wave >> 2;
;     u32x4 kr[TY == 2 ? 4 : 1], vr[TY == 2 ? 8 : 1];
;     if constexpr (TY == 2) { const size_t rowq = (size_t)b * 2048 + (sc * NB) * 64;
;         ld_rows<256>(kr, Pb + rowq * NO + O_K + h * 256, NO, tid); ld_T<512>(vr, Pb + rowq * NO + voff, NO, wave, lane); }
;     for (int j = 0; j <= jc; ++j) { const size_t rowj = (size_t)b * 2048 + (sc * NB + j) * 64;
;         if constexpr (TY == 2) { st_rows<256>(KTs, PQ, kr, tid); st_T<512>(VTs, 72, vr, wave, lane); }
;         else { stage_rows<DK>(KTs, PQ, (const bf16_t*)(p.ws + WS_KT) + rowj * 768 + ecol, 768, tid);
;                stage_T<DV>(VTs, 72, Pb + rowj * PP + voff, PP, wave, lane); }
	s_movk_i32 s38, 0x90
	s_bfe_u32 s1, s1, 0x30002
	s_add_i32 s0, s36, s0
	s_mul_i32 s21, s1, 0x300000
	s_and_b32 s0, s0, 3
	v_mul_lo_u32 v202, v61, s38
	s_mul_hi_i32 s38, s20, 0x1800000
	s_mul_i32 s20, s20, 0x1800000
	s_add_u32 s39, s20, s21
	s_addc_u32 s21, s38, 0
	s_lshl_b32 s20, s37, 4
	s_and_b32 s20, s20, 0x600
	v_mad_i64_i32 v[68:69], s[10:11], v62, s56, 0
	s_or_b32 s20, s39, s20
	v_lshlrev_b32_e32 v217, 1, v60
	v_lshl_add_u64 v[60:61], s[20:21], 0, v[68:69]
	v_readlane_b32 s76, v254, 55
	v_mad_i64_i32 v[62:63], s[10:11], v63, s56, 0
	v_lshl_add_u64 v[42:43], v[42:43], 1, v[60:61]
	v_readlane_b32 s77, v254, 56
	v_mad_i64_i32 v[70:71], s[10:11], v64, s56, 0
	s_nop 0
	v_lshl_add_u64 v[140:141], s[76:77], 0, v[42:43]
	v_lshl_add_u64 v[42:43], s[20:21], 0, v[62:63]
	v_lshl_add_u64 v[42:43], v[44:45], 1, v[42:43]
	v_lshl_add_u64 v[142:143], s[76:77], 0, v[42:43]
	v_lshl_add_u64 v[42:43], s[20:21], 0, v[70:71]
	v_mad_i64_i32 v[64:65], s[10:11], v65, s56, 0
	v_lshl_add_u64 v[42:43], v[50:51], 1, v[42:43]
	v_lshl_add_u64 v[144:145], s[76:77], 0, v[42:43]
	v_lshl_add_u64 v[42:43], s[20:21], 0, v[64:65]
	s_lshl_b32 s20, s37, 5
	s_and_b32 s20, s20, 0xc00
	v_lshl_add_u64 v[42:43], v[52:53], 1, v[42:43]
	s_or_b32 s20, s39, s20
	v_lshl_add_u64 v[146:147], s[76:77], 0, v[42:43]
	v_mov_b32_e32 v42, s20
	v_mov_b32_e32 v43, s21
	v_lshl_add_u64 v[42:43], v[58:59], 1, v[42:43]
	v_readlane_b32 s20, v254, 57
	s_movk_i32 s10, 0xfff
	v_lshl_add_u64 v[42:43], v[42:43], 0, v[16:17]
	v_readlane_b32 s21, v254, 58
	s_mul_i32 s9, s0, 0xc0000
	v_cmp_lt_i32_e64 s[0:1], s57, v157
	v_or_b32_e32 v215, 16, v157
	v_cmp_lt_i32_e64 s[10:11], s10, v157
	v_or_b32_e32 v214, 17, v157
	v_or_b32_e32 v211, 18, v157
	v_or_b32_e32 v212, 3, v157
	v_or_b32_e32 v213, 19, v157
	v_lshl_add_u64 v[148:149], s[20:21], 0, v[42:43]
	v_mov_b32_e32 v42, 0
	s_waitcnt vmcnt(0)
	v_mov_b64_e32 v[100:101], v[56:57]
	v_mov_b64_e32 v[132:133], v[32:33]
	v_mov_b64_e32 v[128:129], v[36:37]
	v_mov_b64_e32 v[124:125], v[40:41]
	v_mov_b64_e32 v[120:121], v[48:49]
	v_lshlrev_b32_e32 v216, 1, v66
	v_cmp_lt_i32_e32 vcc, s57, v215
	v_cmp_lt_i32_e64 s[12:13], s57, v214
	v_cmp_lt_i32_e64 s[14:15], s57, v211
	v_cmp_lt_i32_e64 s[16:17], s57, v212
	v_cmp_lt_i32_e64 s[18:19], s57, v213
	v_mul_u32_u24_e32 v201, 0x90, v150
	v_add_u32_e32 v160, 0x900, v202
	v_add_u32_e32 v159, 0x1200, v202
	v_add_u32_e32 v158, 0x1b00, v202
	s_mov_b64 s[38:39], 0
	s_and_b64 s[20:21], s[10:11], s[0:1]
	v_mov_b64_e32 v[98:99], v[54:55]
	v_mov_b64_e32 v[130:131], v[30:31]
	v_mov_b64_e32 v[126:127], v[34:35]
	v_mov_b64_e32 v[122:123], v[38:39]
	v_mov_b64_e32 v[118:119], v[46:47]
	v_mov_b32_e32 v43, v42
	v_mov_b32_e32 v44, v42
	v_mov_b32_e32 v45, v42
	v_mov_b32_e32 v50, v42
	v_mov_b32_e32 v51, v42
	v_mov_b32_e32 v52, v42
	v_mov_b32_e32 v53, v42
	v_mov_b32_e32 v58, v42
	v_mov_b32_e32 v59, v42
	v_mov_b32_e32 v60, v42
	v_mov_b32_e32 v61, v42
	v_mov_b32_e32 v62, v42
	v_mov_b32_e32 v63, v42
	v_mov_b32_e32 v64, v42
	v_mov_b32_e32 v65, v42
	v_mov_b32_e32 v66, v42
	v_mov_b32_e32 v67, v42
	v_mov_b32_e32 v68, v42
	v_mov_b32_e32 v69, v42
	v_mov_b32_e32 v70, v42
	v_mov_b32_e32 v71, v42
	v_mov_b32_e32 v72, v42
	v_mov_b32_e32 v73, v42
	v_mov_b32_e32 v74, v42
	v_mov_b32_e32 v75, v42
	v_mov_b32_e32 v76, v42
	v_mov_b32_e32 v77, v42
	v_mov_b32_e32 v78, v42
	v_mov_b32_e32 v79, v42
	v_mov_b32_e32 v80, v42
	v_mov_b32_e32 v81, v42
	v_mov_b32_e32 v82, v42
	v_mov_b32_e32 v83, v42
	v_mov_b32_e32 v84, v42
	v_mov_b32_e32 v85, v42
	v_mov_b32_e32 v86, v42
	v_mov_b32_e32 v87, v42
	v_mov_b32_e32 v88, v42
	v_mov_b32_e32 v89, v42
	v_mov_b32_e32 v90, v42
	v_mov_b32_e32 v91, v42
	v_mov_b32_e32 v92, v42
	v_mov_b32_e32 v93, v42
	v_mov_b32_e32 v94, v42
	v_mov_b32_e32 v95, v42
	v_mov_b32_e32 v96, v42
	v_mov_b32_e32 v97, v42
	v_mov_b32_e32 v102, v42
	v_mov_b32_e32 v103, v42
	v_mov_b32_e32 v104, v42
	v_mov_b32_e32 v105, v42
	v_mov_b32_e32 v106, v42
	v_mov_b32_e32 v107, v42
	v_mov_b32_e32 v108, v42
	v_mov_b32_e32 v109, v42
	v_mov_b32_e32 v110, v42
	v_mov_b32_e32 v111, v42
	v_mov_b32_e32 v112, v42
	v_mov_b32_e32 v113, v42
	v_mov_b32_e32 v114, v42
	v_mov_b32_e32 v115, v42
	v_mov_b32_e32 v116, v42
	v_mov_b32_e32 v117, v42
	v_and_b32_e32 v200, 31, v161
	v_bfe_u32 v218, v161, 6, 1
	v_lshl_or_b32 v200, v218, 5, v200
	v_lshrrev_b32_e32 v219, 7, v161
	v_bfe_u32 v220, v161, 5, 1
	v_lshl_or_b32 v219, v219, 1, v220
	v_and_b32_e32 v220, 3, v200
	v_bfe_u32 v221, v200, 2, 2
	v_lshl_or_b32 v220, v220, 2, v221
	v_and_b32_e32 v221, 7, v220
	v_xor_b32_e32 v221, v219, v221
	v_lshrrev_b32_e32 v220, 3, v220
	v_lshlrev_b32_e32 v200, 8, v200
	v_lshl_add_u32 v200, v221, 4, v200
	v_lshl_add_u32 v200, v220, 7, v200
	v_add_u32_e32 v190, 0x10800, v200
	v_xor_b32_e32 v191, 0x80, v190
	v_bfe_u32 v200, v161, 4, 2
	v_bfe_u32 v218, v161, 2, 2
	v_and_b32_e32 v219, 3, v161
	v_lshl_or_b32 v220, v200, 3, v218
	v_lshlrev_b32_e32 v221, 1, v200
	v_and_b32_e32 v221, 3, v221
	v_lshl_or_b32 v221, v218, 2, v221
	v_bfe_u32 v200, v161, 6, 1
	v_lshrrev_b32_e32 v218, 1, v219
	v_lshl_or_b32 v200, v200, 3, v218
	v_xor_b32_e32 v200, v200, v221
	v_and_b32_e32 v219, 1, v219
	v_lshlrev_b32_e32 v220, 8, v220
	v_lshl_add_u32 v220, v200, 4, v220
	v_lshl_add_u32 v220, v219, 3, v220
	v_lshrrev_b32_e32 v200, 7, v161
	v_lshl_add_u32 v220, v200, 14, v220
	v_add_u32_e32 v192, 0x10800, v220
	v_xor_b32_e32 v193, 16, v192
	v_add_u32_e32 v193, 0x400, v193
	v_xor_b32_e32 v194, 32, v192
	v_xor_b32_e32 v195, 32, v193
	v_xor_b32_e32 v196, 64, v192
	v_xor_b32_e32 v197, 64, v193
	v_xor_b32_e32 v198, 0x60, v192
	v_xor_b32_e32 v199, 0x60, v193
; #define LAS __attribute__((address_space(3)))
; __device__ __forceinline__ unsigned pk2(float lo, float hi) { return pg8::cvt_pk_bf16(lo, hi); }
; __device__ __forceinline__ f32x4 mma16(bf16x8 a, bf16x8 b, f32x4 c) { return __builtin_amdgcn_mfma_f32_16x16x32_bf16(a, b, c, 0, 0, 0); }
; #define BSYNC() do { asm volatile("s_waitcnt vmcnt(0) lgkmcnt(0)" ::: "memory"); __syncthreads(); } while (0)
; template <int TY> __device__ __forceinline__ void mc_item(const Params& p, ldsp lds, int item) {
;     ...
;     for (int j = 0; j <= jc; ++j) { const size_t rowj = (size_t)b * 2048 + (sc * NB + j) * 64;
;         if constexpr (TY == 2) { st_rows<256>(KTs, PQ, kr, tid); st_T<512>(VTs, 72, vr, wave, lane); }
;         else { stage_rows<DK>(KTs, PQ, (const bf16_t*)(p.ws + WS_KT) + rowj * 768 + ecol, 768, tid);
;                stage_T<DV>(VTs, 72, Pb + rowj * PP + voff, PP, wave, lane); }
;         if constexpr (TY == 2) { __syncthreads(); if (j < jc) { const size_t rown = rowj + 64; ld_rows<256>(kr, Pb + rown * NO + O_K + h * 256, NO, tid); ld_T<512>(vr, Pb + rown * NO + voff, NO, wave, lane); } }
;         else BSYNC();
;         { f32x4 c0 = (f32x4){0.f, 0.f, 0.f, 0.f}, c1 = c0;
; #pragma unroll
;           for (int ks = 0; ks < DK / 32; ++ks) { const bf16x8 bq = ldfrag(QX, (16 * tt + l15) * PQ + 32 * ks + 8 * q4);
;               c0 = mma16(ldfrag(KTs, (16 * (2 * sp) + l15) * PQ + 32 * ks + 8 * q4), bq, c0);
;               c1 = mma16(ldfrag(KTs, (16 * (2 * sp + 1) + l15) * PQ + 32 * ks + 8 * q4), bq, c1); }
;           const int t = 16 * tt + l15;
;           const int tl = (j == jc) ? t : 4096;
; #pragma unroll
;           for (int jj = 0; jj < 4; ++jj) { if (32 * sp + 4 * q4 + jj > tl) c0[jj] = 0.f; if (32 * sp + 16 + 4 * q4 + jj > tl) c1[jj] = 0.f; }
;           u32x2 w; w.x = pk2(c0[0], c0[1]); w.y = pk2(c0[2], c0[3]); *(LAS u32x2*)(Pm + (size_t)(t * 72 + 32 * sp + 4 * q4) * 2) = w;
;           w.x = pk2(c1[0], c1[1]); w.y = pk2(c1[2], c1[3]); *(LAS u32x2*)(Pm + (size_t)(t * 72 + 32 * sp + 16 + 4 * q4) * 2) = w; }
;         if constexpr (TY == 2) __syncthreads(); else BSYNC();
.LBB0_880:
	v_add_u32_e32 v16, v206, v203
	s_waitcnt vmcnt(11)
	ds_write_b128 v16, v[130:133] offset:33792
	v_add_u32_e32 v16, v207, v204
	s_waitcnt vmcnt(10)
	ds_write_b128 v16, v[126:129] offset:33792
	v_add_u32_e32 v16, v208, v205
	s_waitcnt vmcnt(9)
	ds_write_b128 v16, v[122:125] offset:33792
	v_add_u32_e32 v16, v210, v209
	s_waitcnt vmcnt(8)
	ds_write_b128 v16, v[118:121] offset:33792
	s_waitcnt vmcnt(7)
	ds_write_b128 v190, v[26:29]
	s_waitcnt vmcnt(6)
	ds_write_b128 v191, v[22:25]
	s_waitcnt vmcnt(5)
	ds_write_b128 v190, v[18:21] offset:16384
	s_waitcnt vmcnt(4)
	ds_write_b128 v191, v[12:15] offset:16384
	s_waitcnt vmcnt(3)
	ds_write_b128 v190, v[8:11] offset:32768
	s_waitcnt vmcnt(2)
	ds_write_b128 v191, v[4:7] offset:32768
	s_waitcnt vmcnt(1)
	ds_write_b128 v190, v[0:3] offset:49152
	s_waitcnt vmcnt(0)
	ds_write_b128 v191, v[98:101] offset:49152
	v_lshl_add_u64 v[0:1], v[140:141], 0, s[38:39]
	s_waitcnt lgkmcnt(0)
	s_barrier
	global_load_dwordx4 v[130:133], v[0:1], off
	v_lshl_add_u64 v[0:1], v[142:143], 0, s[38:39]
	global_load_dwordx4 v[126:129], v[0:1], off
	v_lshl_add_u64 v[0:1], v[144:145], 0, s[38:39]
	global_load_dwordx4 v[122:125], v[0:1], off
	v_lshl_add_u64 v[0:1], v[146:147], 0, s[38:39]
	v_lshl_add_u64 v[98:99], v[148:149], 0, s[38:39]
	v_add_u32_e32 v16, 0, v163
	v_add_u32_e32 v166, 0, v217
	v_add_u32_e32 v167, 0, v216
	global_load_dwordx4 v[118:121], v[0:1], off
	global_load_dwordx4 v[26:29], v[98:99], off offset:-512
	global_load_dwordx4 v[22:25], v[98:99], off offset:-384
	global_load_dwordx4 v[18:21], v[98:99], off offset:-256
	global_load_dwordx4 v[12:15], v[98:99], off offset:-128
	global_load_dwordx4 v[8:11], v[98:99], off
	global_load_dwordx4 v[4:7], v[98:99], off offset:128
	global_load_dwordx4 v[0:3], v[98:99], off offset:256
	s_nop 0
	global_load_dwordx4 v[98:101], v[98:99], off offset:384
	ds_read_b128 v[134:137], v16
	ds_read_b128 v[172:175], v166 offset:33792
	ds_read_b128 v[176:179], v167 offset:33792
	s_waitcnt lgkmcnt(1)
	v_mfma_f32_16x16x32_bf16 v[172:175], v[172:175], v[134:137], 0
	s_add_u32 s38, s38, 0xc0000
	s_addc_u32 s39, s39, 0
	s_cmp_eq_u32 s9, s38
	s_waitcnt lgkmcnt(0)
	v_mfma_f32_16x16x32_bf16 v[134:137], v[176:179], v[134:137], 0
	ds_read_b128 v[176:179], v16 offset:64
	ds_read_b128 v[180:183], v166 offset:33856
	s_waitcnt lgkmcnt(0)
	v_mfma_f32_16x16x32_bf16 v[172:175], v[180:183], v[176:179], v[172:175]
	ds_read_b128 v[180:183], v167 offset:33856
	s_waitcnt lgkmcnt(0)
	v_mfma_f32_16x16x32_bf16 v[134:137], v[180:183], v[176:179], v[134:137]
	ds_read_b128 v[176:179], v16 offset:128
	ds_read_b128 v[180:183], v166 offset:33920
	s_waitcnt lgkmcnt(0)
	v_mfma_f32_16x16x32_bf16 v[172:175], v[180:183], v[176:179], v[172:175]
	ds_read_b128 v[180:183], v167 offset:33920
	s_waitcnt lgkmcnt(0)
	v_mfma_f32_16x16x32_bf16 v[134:137], v[180:183], v[176:179], v[134:137]
	ds_read_b128 v[176:179], v16 offset:192
	ds_read_b128 v[180:183], v166 offset:33984
	s_waitcnt lgkmcnt(0)
	v_mfma_f32_16x16x32_bf16 v[172:175], v[180:183], v[176:179], v[172:175]
	ds_read_b128 v[180:183], v167 offset:33984
	s_waitcnt lgkmcnt(0)
	v_mfma_f32_16x16x32_bf16 v[134:137], v[180:183], v[176:179], v[134:137]
	ds_read_b128 v[176:179], v16 offset:256
	ds_read_b128 v[180:183], v166 offset:34048
	s_waitcnt lgkmcnt(0)
	v_mfma_f32_16x16x32_bf16 v[172:175], v[180:183], v[176:179], v[172:175]
	ds_read_b128 v[180:183], v167 offset:34048
	s_waitcnt lgkmcnt(0)
	v_mfma_f32_16x16x32_bf16 v[134:137], v[180:183], v[176:179], v[134:137]
	ds_read_b128 v[176:179], v16 offset:320
	ds_read_b128 v[180:183], v166 offset:34112
	s_waitcnt lgkmcnt(0)
	v_mfma_f32_16x16x32_bf16 v[172:175], v[180:183], v[176:179], v[172:175]
	ds_read_b128 v[180:183], v167 offset:34112
	s_waitcnt lgkmcnt(0)
	v_mfma_f32_16x16x32_bf16 v[134:137], v[180:183], v[176:179], v[134:137]
	ds_read_b128 v[176:179], v16 offset:384
	ds_read_b128 v[180:183], v166 offset:34176
	s_waitcnt lgkmcnt(0)
	v_mfma_f32_16x16x32_bf16 v[172:175], v[180:183], v[176:179], v[172:175]
	ds_read_b128 v[180:183], v167 offset:34176
	s_waitcnt lgkmcnt(0)
	v_mfma_f32_16x16x32_bf16 v[134:137], v[180:183], v[176:179], v[134:137]
	ds_read_b128 v[176:179], v16 offset:448
	ds_read_b128 v[180:183], v166 offset:34240
	v_mov_b32_e32 v16, s41
	s_waitcnt lgkmcnt(0)
	v_mfma_f32_16x16x32_bf16 v[172:175], v[180:183], v[176:179], v[172:175]
	ds_read_b128 v[180:183], v167 offset:34240
	s_waitcnt lgkmcnt(0)
	v_mfma_f32_16x16x32_bf16 v[134:137], v[180:183], v[176:179], v[134:137]
	v_mov_b32_e32 v176, s41
	s_nop 3
	v_cndmask_b32_e64 v16, v172, v16, s[20:21]
	v_cndmask_b32_e64 v168, v175, 0, s[16:17]
	s_nop 0
	v_cndmask_b32_e32 v166, v134, v176, vcc
	v_cndmask_b32_e64 v134, v173, 0, s[10:11]
	v_cndmask_b32_e64 v167, v135, 0, s[12:13]
	v_cndmask_b32_e64 v135, v174, 0, s[10:11]
	v_cvt_pk_bf16_f32 v134, v16, v134
	v_add_u32_e32 v16, 0, v156
	v_cvt_pk_bf16_f32 v135, v135, v168
	v_add_u32_e32 v16, 0x22800, v16
	v_cndmask_b32_e64 v136, v136, 0, s[14:15]
	v_cndmask_b32_e64 v137, v137, 0, s[18:19]
	ds_write_b64 v16, v[134:135]
	v_cvt_pk_bf16_f32 v134, v166, v167
	v_cvt_pk_bf16_f32 v135, v136, v137
	ds_write_b64 v16, v[134:135] offset:32
	v_add_u32_e32 v16, v154, v201
	v_add_u32_e32 v166, v139, v202
	s_waitcnt lgkmcnt(0)
	s_barrier
; __device__ __forceinline__ f32x4 mma16(bf16x8 a, bf16x8 b, f32x4 c) { return __builtin_amdgcn_mfma_f32_16x16x32_bf16(a, b, c, 0, 0, 0); }
; #define BSYNC() do { asm volatile("s_waitcnt vmcnt(0) lgkmcnt(0)" ::: "memory"); __syncthreads(); } while (0)
; template <int TY> __device__ __forceinline__ void mc_item(const Params& p, ldsp lds, int item) {
;     ...
; #pragma unroll
;         for (int ks = 0; ks < 2; ++ks) { bf16x8 pb[4];
; #pragma unroll
;             for (int tk = 0; tk < 4; ++tk) pb[tk] = ldfrag(Pm, (16 * tk + l15) * 72 + 32 * ks + 8 * q4);
; #pragma unroll
;             for (int ei = 0; ei < ET; ++ei) { const bf16x8 va = ldfrag(VTs, (16 * (wave * ET + ei) + l15) * 72 + 32 * ks + 8 * q4);
; #pragma unroll
;                 for (int tk = 0; tk < 4; ++tk) acc[ei][tk] = mma16(va, pb[tk], acc[ei][tk]); } }
;         if constexpr (TY == 2) __syncthreads(); else BSYNC(); }
	ds_read_b128 v[134:137], v16
	ds_read_b128 v[172:175], v16 offset:2304
	ds_read_b128 v[176:179], v16 offset:4608
	ds_read_b128 v[180:183], v16 offset:6912
	ds_read_b64_tr_b16 v[186:187], v192
	ds_read_b64_tr_b16 v[188:189], v193
	s_waitcnt lgkmcnt(0)
	v_mfma_f32_16x16x32_bf16 v[62:65], v[186:189], v[134:137], v[62:65]
	v_mfma_f32_16x16x32_bf16 v[58:61], v[186:189], v[172:175], v[58:61]
	v_mfma_f32_16x16x32_bf16 v[50:53], v[186:189], v[176:179], v[50:53]
	v_mfma_f32_16x16x32_bf16 v[42:45], v[186:189], v[180:183], v[42:45]
	ds_read_b64_tr_b16 v[186:187], v194
	ds_read_b64_tr_b16 v[188:189], v195
	s_waitcnt lgkmcnt(0)
	v_mfma_f32_16x16x32_bf16 v[66:69], v[186:189], v[134:137], v[66:69]
	v_mfma_f32_16x16x32_bf16 v[70:73], v[186:189], v[172:175], v[70:73]
	v_mfma_f32_16x16x32_bf16 v[74:77], v[186:189], v[176:179], v[74:77]
	v_mfma_f32_16x16x32_bf16 v[78:81], v[186:189], v[180:183], v[78:81]
	ds_read_b64_tr_b16 v[186:187], v196
	ds_read_b64_tr_b16 v[188:189], v197
	s_waitcnt lgkmcnt(0)
	v_mfma_f32_16x16x32_bf16 v[82:85], v[186:189], v[134:137], v[82:85]
	v_mfma_f32_16x16x32_bf16 v[86:89], v[186:189], v[172:175], v[86:89]
	v_mfma_f32_16x16x32_bf16 v[90:93], v[186:189], v[176:179], v[90:93]
	v_mfma_f32_16x16x32_bf16 v[94:97], v[186:189], v[180:183], v[94:97]
	ds_read_b64_tr_b16 v[186:187], v198
	ds_read_b64_tr_b16 v[188:189], v199
	s_waitcnt lgkmcnt(0)
	v_mfma_f32_16x16x32_bf16 v[102:105], v[186:189], v[134:137], v[102:105]
	v_mfma_f32_16x16x32_bf16 v[106:109], v[186:189], v[172:175], v[106:109]
	v_mfma_f32_16x16x32_bf16 v[110:113], v[186:189], v[176:179], v[110:113]
	v_mfma_f32_16x16x32_bf16 v[114:117], v[186:189], v[180:183], v[114:117]
	ds_read_b128 v[134:137], v16 offset:64
	ds_read_b128 v[172:175], v16 offset:2368
	ds_read_b128 v[176:179], v16 offset:4672
	ds_read_b128 v[180:183], v16 offset:6976
	ds_read_b64_tr_b16 v[186:187], v192 offset:8192
	ds_read_b64_tr_b16 v[188:189], v193 offset:8192
	s_waitcnt lgkmcnt(0)
	v_mfma_f32_16x16x32_bf16 v[62:65], v[186:189], v[134:137], v[62:65]
	v_mfma_f32_16x16x32_bf16 v[58:61], v[186:189], v[172:175], v[58:61]
	v_mfma_f32_16x16x32_bf16 v[50:53], v[186:189], v[176:179], v[50:53]
	v_mfma_f32_16x16x32_bf16 v[42:45], v[186:189], v[180:183], v[42:45]
	ds_read_b64_tr_b16 v[186:187], v194 offset:8192
	ds_read_b64_tr_b16 v[188:189], v195 offset:8192
	s_waitcnt lgkmcnt(0)
	v_mfma_f32_16x16x32_bf16 v[66:69], v[186:189], v[134:137], v[66:69]
	v_mfma_f32_16x16x32_bf16 v[70:73], v[186:189], v[172:175], v[70:73]
	v_mfma_f32_16x16x32_bf16 v[74:77], v[186:189], v[176:179], v[74:77]
	v_mfma_f32_16x16x32_bf16 v[78:81], v[186:189], v[180:183], v[78:81]
	ds_read_b64_tr_b16 v[186:187], v196 offset:8192
	ds_read_b64_tr_b16 v[188:189], v197 offset:8192
	s_waitcnt lgkmcnt(0)
	v_mfma_f32_16x16x32_bf16 v[82:85], v[186:189], v[134:137], v[82:85]
	v_mfma_f32_16x16x32_bf16 v[86:89], v[186:189], v[172:175], v[86:89]
	v_mfma_f32_16x16x32_bf16 v[90:93], v[186:189], v[176:179], v[90:93]
	v_mfma_f32_16x16x32_bf16 v[94:97], v[186:189], v[180:183], v[94:97]
	ds_read_b64_tr_b16 v[186:187], v198 offset:8192
	ds_read_b64_tr_b16 v[188:189], v199 offset:8192
	s_waitcnt lgkmcnt(0)
	s_barrier
	v_mfma_f32_16x16x32_bf16 v[102:105], v[186:189], v[134:137], v[102:105]
	v_mfma_f32_16x16x32_bf16 v[106:109], v[186:189], v[172:175], v[106:109]
	v_mfma_f32_16x16x32_bf16 v[110:113], v[186:189], v[176:179], v[110:113]
	v_mfma_f32_16x16x32_bf16 v[114:117], v[186:189], v[180:183], v[114:117]
	s_cbranch_scc0 .LBB0_880
	s_movk_i32 s9, 0x90
	s_branch .LBB0_883
